# fix-up half-units taken longest carry chain first (chunk 63 down to 0) instead of ascending
# speedup vs baseline: 1.0145x; 1.0059x over previous
; __device__ __forceinline__ int fresh_tid() { int t = threadIdx.x; asm volatile("" : "+v"(t)); return t; }
; __device__ __forceinline__ void lru_fixup_unit(const Params& p, int ck) {
;     const int tid = fresh_tid(), ch = tid * 2;
;     unsigned char* ws = p.ws;
;     const bf16_t* GG = (const bf16_t*)(ws + WS_GG);
;     const float* HL = (const float*)(ws + WS_HL); const float* PP = (const float*)(ws + WS_PP); const float* SUMA = (const float*)(ws + WS_SUMA); const float* SUMH = (const float*)(ws + WS_SUMH);
;     bf16_t* CATB = (bf16_t*)(ws + WS_CATB); float* PS = (float*)(ws + WS_PS);
;     typedef float f32x2 __attribute__((ext_vector_type(2)));
;     f32x2 carry = (f32x2){0.f, 0.f};
;     const bool prompt = ck < LRU_PCHUNK;
;     if (prompt) {
;         const int b = ck / LRU_CPB, kk = ck % LRU_CPB;
; #pragma unroll 16
;         for (int j = 0; j < kk; ++j) {
;             const f32x2 A = *(const f32x2*)(SUMA + (size_t)(b * LRU_CPB + j) * DRNN + ch), Hh = *(const f32x2*)(SUMH + (size_t)(b * LRU_CPB + j) * DRNN + ch);
;             carry = A * carry + Hh;
;         }
;     }
;     ...
;         const unsigned idx = wq_next(ctr, lds);
;         if (idx >= (unsigned)(MS + LRU_NCHUNK)) break;
;         if (idx < (unsigned)MS) sample_row_unit(p, lds, (int)idx); else lru_fixup_unit(p, (int)idx - MS);
.LBB0_2893:
	s_or_b64 exec, exec, s[40:41]
	s_waitcnt lgkmcnt(0)
	s_barrier
	ds_read_b32 v2, v1
	s_mov_b64 s[40:41], -1
	s_waitcnt lgkmcnt(0)
	v_cmp_lt_u32_e32 vcc, s77, v2
	v_readfirstlane_b32 s44, v2
	s_cbranch_vccnz .LBB0_2888
	s_cmpk_gt_u32 s44, 0x7f
	s_cbranch_scc0 .LBB0_2910
	v_mov_b32_e32 v2, v0
	s_add_i32 s40, s44, 0xffffff80
	s_and_b32 s45, s40, 1
	s_lshr_b32 s40, s40, 1
	s_cmpk_gt_u32 s40, 0x7f
	s_cbranch_scc1 .Lfx_nomap
	s_and_b32 s41, s40, 1
	s_lshl_b32 s41, s41, 6
	s_lshr_b32 s40, s40, 1
	s_sub_i32 s40, 63, s40
	s_or_b32 s40, s40, s41
.Lfx_nomap:
	s_cmpk_gt_u32 s40, 0x7f
	v_lshlrev_b32_e32 v6, 1, v2
	v_mov_b32_e32 v2, 0
	v_mov_b32_e32 v3, 0
	s_cbranch_scc1 .LBB0_2905
	s_and_b32 s16, s40, 63
	s_cmp_eq_u32 s16, 0
	s_cbranch_scc1 .LBB0_2905
	s_and_b32 s41, s40, 64
	s_lshl_b32 s41, s41, 12
	s_add_u32 s78, s8, s41
	s_addc_u32 s79, s9, 0
	s_add_u32 s42, s10, s41
	s_addc_u32 s43, s11, 0
	v_lshlrev_b32_e32 v4, 2, v6
